# attention: running-max reference folded into QK MFMA C operand (S-ref), per-element v_sub removed from PV section; V addr rebase
# speedup vs baseline: 1.0104x; 1.0104x over previous
; DEV int get_tid() { int t = threadIdx.x; asm volatile("" : "+v"(t)); return t; }
; DEV void attn_item(const Params& p, int layer, int h, int qb, float lam, bf16_t* lds) {
;     ...
;   const int tid = get_tid(), lane = tid & 63, wave = tid >> 6;
;   const int lr = lane & 15, lg = lane >> 4;
;   const int grp = wave >> 2, wq = wave & 3;
;   const int t0 = qb * 128;
;   const int lrow = tid >> 4, lc8 = (tid & 15) * 8;
;   const bf16_t* gq = DQ + (size_t)(t0 + wq * 32 + lr) * 1024 + h * 128 + grp * 64 + lg * 8;
;   const bf16x8 a00 = *(const bf16x8*)(gq);
;   const bf16x8 a01 = *(const bf16x8*)(gq + 32);
;   const bf16x8 a10 = *(const bf16x8*)(gq + (size_t)16 * 1024);
;   const bf16x8 a11 = *(const bf16x8*)(gq + (size_t)16 * 1024 + 32);
;   f32x4 o[2][8];
; #pragma unroll
;   for (int i = 0; i < 2; i++)
; #pragma unroll
;     for (int j = 0; j < 8; j++) o[i][j] = (f32x4){0.f, 0.f, 0.f, 0.f};
;   float mrun0 = -1e30f, mrun1 = -1e30f, lrun0 = 0.f, lrun1 = 0.f;
;   u32x4 rk0, rk1, rk2, rk3, rv0, rv1, rv2, rv3;
;   const unsigned ko = (unsigned)(lrow * 1024 + h * 128 + lc8);
;   const unsigned vo = (unsigned)((h * 128 + lrow) * LT + lc8);
;     ...
;   ALOAD(0)
;   const int qrow0 = t0 + wq * 32 + lr;
;   __syncthreads();
;   ASTORE(KV + lrow * PS + lc8)
;   {
;     const int kb1 = qb > 0 ? 1 : 0;
;     ALOAD(kb1)
;   }
;   __syncthreads();
.LBB0_706:
	v_mov_b32_e32 v224, v181
	s_ashr_i32 s0, s2, 3
	s_sub_i32 s76, 64, s0
	v_lshrrev_b32_e32 v2, 1, v224
	v_and_b32_e32 v226, 0x60, v2
	v_and_b32_e32 v222, 15, v224
	v_lshlrev_b32_e32 v0, 3, v224
	v_lshl_or_b32 v223, s76, 7, v226
	s_lshl_b32 s1, s2, 7
	v_ashrrev_i32_e32 v84, 4, v224
	v_or_b32_e32 v184, v223, v222
	v_mov_b32_e32 v185, v1
	v_readlane_b32 s6, v254, 55
	s_and_b32 s75, s1, 0x380
	v_and_b32_e32 v85, 0x78, v0
	v_lshlrev_b32_e32 v0, 10, v84
	v_ashrrev_i32_e32 v225, 8, v224
	v_lshlrev_b64 v[2:3], 11, v[184:185]
	v_readlane_b32 s7, v254, 56
	v_or3_b32 v186, v0, s75, v85
	v_add_u32_e32 v0, s75, v84
	s_movk_i32 s1, 0x2080
	v_lshl_add_u64 v[2:3], s[6:7], 0, v[2:3]
	s_lshl_b32 s82, s75, 1
	v_lshlrev_b32_e32 v4, 6, v225
	v_mul_lo_u32 v0, v0, s1
	v_lshl_add_u64 v[2:3], v[2:3], 0, s[82:83]
	v_ashrrev_i32_e32 v5, 31, v4
	v_or_b32_e32 v188, v0, v85
	v_mov_b32_e32 v187, v1
	v_add_u32_e32 v0, 0x8000, v186
	v_lshl_add_u64 v[2:3], v[4:5], 1, v[2:3]
	v_lshl_add_u64 v[4:5], v[186:187], 1, s[78:79]
	v_lshl_add_u64 v[6:7], v[0:1], 1, s[78:79]
	v_add_u32_e32 v0, 0x10000, v186
	global_load_dwordx4 v[52:55], v[4:5], off
	global_load_dwordx4 v[56:59], v[6:7], off
	v_lshl_add_u64 v[4:5], v[0:1], 1, s[78:79]
	v_add_u32_e32 v0, 0x18000, v186
	v_lshl_add_u64 v[6:7], v[0:1], 1, s[78:79]
	v_mov_b32_e32 v189, v1
	v_add_u32_e32 v0, 0x41000, v188
	global_load_dwordx4 v[60:63], v[4:5], off
	global_load_dwordx4 v[64:67], v[6:7], off
	v_lshl_add_u64 v[4:5], v[188:189], 1, s[70:71]
	v_lshl_add_u64 v[6:7], v[0:1], 1, s[70:71]
	v_add_u32_e32 v0, 0x82000, v188
	v_and_b32_e32 v182, 48, v224
	v_mov_b32_e32 v183, v1
	global_load_dwordx4 v[68:71], v[4:5], off
	global_load_dwordx4 v[72:75], v[6:7], off
	v_lshl_add_u64 v[4:5], v[0:1], 1, s[70:71]
	v_add_u32_e32 v0, 0xc3000, v188
	global_load_dwordx4 v[76:79], v[4:5], off
	v_lshl_add_u64 v[4:5], v[0:1], 1, s[70:71]
	v_lshl_add_u64 v[2:3], v[2:3], 0, v[182:183]
	s_mov_b32 s1, 0x8000
	s_cmp_eq_u32 s0, 64
	global_load_dwordx4 v[80:83], v[4:5], off
	s_nop 0
	global_load_dwordx4 v[4:7], v[2:3], off
	global_load_dwordx4 v[8:11], v[2:3], off offset:64
	v_add_co_u32_e32 v2, vcc, s1, v2
	s_cselect_b32 s1, 0, 0x20000
	v_add_u32_e32 v0, s1, v186
	v_addc_co_u32_e32 v3, vcc, 0, v3, vcc
	v_add_u32_e32 v20, 0x8000, v0
	v_mov_b32_e32 v21, v1
	global_load_dwordx4 v[12:15], v[2:3], off
	global_load_dwordx4 v[16:19], v[2:3], off offset:64
	v_lshl_add_u64 v[2:3], v[0:1], 1, s[78:79]
	v_lshl_add_u64 v[24:25], v[20:21], 1, s[78:79]
	s_barrier
	global_load_dwordx4 v[20:23], v[2:3], off
	s_nop 0
	global_load_dwordx4 v[24:27], v[24:25], off
	v_add_u32_e32 v2, 0x10000, v0
	v_add_u32_e32 v0, 0x18000, v0
	s_cselect_b32 s1, 0, 0x80
	v_mov_b32_e32 v3, v1
	v_lshl_add_u64 v[32:33], v[0:1], 1, s[78:79]
	v_add_u32_e32 v0, s1, v188
	v_lshl_add_u64 v[2:3], v[2:3], 1, s[78:79]
	v_add_u32_e32 v36, 0x41000, v0
	v_mov_b32_e32 v37, v1
	global_load_dwordx4 v[28:31], v[2:3], off
	s_nop 0
	global_load_dwordx4 v[32:35], v[32:33], off
	v_lshl_add_u64 v[2:3], v[0:1], 1, s[70:71]
	v_lshl_add_u64 v[40:41], v[36:37], 1, s[70:71]
	global_load_dwordx4 v[36:39], v[2:3], off
	s_nop 0
	global_load_dwordx4 v[40:43], v[40:41], off
	v_add_u32_e32 v2, 0x82000, v0
	v_mov_b32_e32 v3, v1
	v_add_u32_e32 v0, 0xc3000, v0
	v_lshl_add_u64 v[2:3], v[2:3], 1, s[70:71]
	v_lshl_add_u64 v[48:49], v[0:1], 1, s[70:71]
	global_load_dwordx4 v[44:47], v[2:3], off
	s_nop 0
	global_load_dwordx4 v[48:51], v[48:49], off
	s_movk_i32 s1, 0x110
	v_mul_lo_u32 v84, v84, s1
	v_lshlrev_b32_e32 v85, 1, v85
	v_add3_u32 v230, 0, v84, v85
	v_and_b32_e32 v0, 15, v181
	v_bfe_u32 v2, v181, 4, 4
	v_not_b32_e32 v3, v2
	v_and_b32_e32 v3, 1, v3
	v_lshlrev_b32_e32 v3, 1, v3
	v_add_u32_e32 v2, 4, v2
	v_bfe_u32 v2, v2, 3, 1
	v_or_b32_e32 v3, v3, v2
	v_xor_b32_e32 v3, v3, v0
	v_sub_u32_e32 v3, v3, v0
	v_lshl_add_u32 v230, v3, 4, v230
	s_waitcnt vmcnt(19)
	ds_write_b128 v230, v[52:55]
	s_waitcnt vmcnt(18)
	ds_write_b128 v230, v[56:59] offset:8704
	s_waitcnt vmcnt(17)
	ds_write_b128 v230, v[60:63] offset:17408
	s_waitcnt vmcnt(16)
	ds_write_b128 v230, v[64:67] offset:26112
	s_mov_b32 s98, 0x11000
	v_and_b32_e32 v0, 15, v181
	v_bfe_u32 v2, v181, 4, 4
	v_not_b32_e32 v54, v2
	v_and_b32_e32 v54, 1, v54
	v_lshlrev_b32_e32 v54, 1, v54
	v_add_u32_e32 v55, 4, v2
	v_bfe_u32 v55, v55, 3, 1
	v_or_b32_e32 v54, v54, v55
	v_xor_b32_e32 v3, v0, v54
	v_lshlrev_b32_e32 v3, 4, v3
	v_sub_u32_e32 v3, v230, v3
	v_add_u32_e32 v3, s98, v3
	v_lshrrev_b32_e32 v55, 2, v0
	v_lshl_add_u32 v3, v55, 6, v3
	v_bfe_u32 v55, v0, 1, 1
	v_lshl_add_u32 v3, v55, 3, v3
	v_and_b32_e32 v55, 1, v0
	v_lshlrev_b32_e32 v55, 1, v55
	v_xor_b32_e32 v55, v55, v54
	v_xor_b32_e32 v54, 1, v55
	v_lshl_add_u32 v52, v55, 4, v3
	v_lshl_add_u32 v53, v54, 4, v3
	v_mov_b32_e32 v204, v52
	v_mov_b32_e32 v205, v53
	v_bfe_u32 v2, v224, 4, 2
	v_not_b32_e32 v3, v222
	v_and_b32_e32 v3, 1, v3
	v_lshlrev_b32_e32 v3, 1, v3
	v_add_u32_e32 v55, 4, v222
	v_bfe_u32 v55, v55, 3, 1
	v_or_b32_e32 v3, v3, v55
	v_xor_b32_e32 v3, v3, v2
	v_lshlrev_b32_e32 v3, 4, v3
	v_readlane_b32 s1, v255, 8
	s_waitcnt vmcnt(15)
	ds_write_b64 v52, v[68:69]
	ds_write_b64 v53, v[70:71]
	s_waitcnt vmcnt(14)
	ds_write_b64 v52, v[72:73] offset:8704
	ds_write_b64 v53, v[74:75] offset:8704
	s_waitcnt vmcnt(13)
	ds_write_b64 v52, v[76:77] offset:17408
	ds_write_b64 v53, v[78:79] offset:17408
	v_and_b32_e32 v0, 63, v224
	v_lshlrev_b32_e32 v54, 7, v225
	v_lshlrev_b32_e32 v183, 2, v2
	s_waitcnt vmcnt(12)
; #define MFMA(a, b, c) __builtin_amdgcn_mfma_f32_16x16x32_bf16(a, b, c, 0, 0, 0)
; DEV float shfl_l(float v, int srclane) { return __int_as_float(__builtin_amdgcn_ds_bpermute(srclane << 2, __float_as_int(v))); }
; DEV void attn_item(const Params& p, int layer, int h, int qb, float lam, bf16_t* lds) {
;     ...
;   f32x4 o[2][8];
; #pragma unroll
;   for (int i = 0; i < 2; i++)
; #pragma unroll
;     for (int j = 0; j < 8; j++) o[i][j] = (f32x4){0.f, 0.f, 0.f, 0.f};
;   float mrun0 = -1e30f, mrun1 = -1e30f, lrun0 = 0.f, lrun1 = 0.f;
;   u32x4 rk0, rk1, rk2, rk3, rv0, rv1, rv2, rv3;
;   const unsigned ko = (unsigned)(lrow * 1024 + h * 128 + lc8);
;   const unsigned vo = (unsigned)((h * 128 + lrow) * LT + lc8);
;     ...
; #pragma unroll
;       for (int j = 0; j < 8; j++)
; #pragma unroll
;         for (int r = 0; r < 4; r++) { const float pv = ex2(s[i][j][r] - mnew); s[i][j][r] = pv; ps += pv; }
;       if (i == 0) { mrun0 = mnew; lrun0 = lrun0 * al[0] + ps; } else { mrun1 = mnew; lrun1 = lrun1 * al[1] + ps; }
;     }
;     if (__builtin_amdgcn_ballot_w64(al[0] != 1.f || al[1] != 1.f) != 0ull) {
; #pragma unroll
;       for (int i = 0; i < 2; i++) {
;         float ao[4];
; #pragma unroll
;         for (int r = 0; r < 4; r++) ao[r] = shfl_l(al[i], lg * 4 + r);
; #pragma unroll
;         for (int je = 0; je < 8; je++)
; #pragma unroll
;           for (int r = 0; r < 4; r++) o[i][je][r] *= ao[r];
;       }
;     }
; #pragma unroll
;     for (int ks = 0; ks < 4; ks++) {
;       union { u32x4 u; bf16x8 v; } pf0, pf1;
;       pf0.u[0] = pack2(s[0][2 * ks][0], s[0][2 * ks][1]);
;       pf0.u[1] = pack2(s[0][2 * ks][2], s[0][2 * ks][3]);
;       pf0.u[2] = pack2(s[0][2 * ks + 1][0], s[0][2 * ks + 1][1]);
;       pf0.u[3] = pack2(s[0][2 * ks + 1][2], s[0][2 * ks + 1][3]);
;       pf1.u[0] = pack2(s[1][2 * ks][0], s[1][2 * ks][1]);
;       pf1.u[1] = pack2(s[1][2 * ks][2], s[1][2 * ks][3]);
;       pf1.u[2] = pack2(s[1][2 * ks + 1][0], s[1][2 * ks + 1][1]);
;       pf1.u[3] = pack2(s[1][2 * ks + 1][2], s[1][2 * ks + 1][3]);
; #pragma unroll
;       for (int je = 0; je < 8; je++) {
;         const bf16_t* vp = vq + je * 16 * PS + ks * 32;
;         union { uint2 u[2]; bf16x8 v; } vf;
;         vf.u[0] = *(const uint2*)vp;
;         vf.u[1] = *(const uint2*)(vp + 16);
;         o[0][je] = MFMA(pf0.v, vf.v, o[0][je]);
;         o[1][je] = MFMA(pf1.v, vf.v, o[1][je]);
;       }
	ds_write_b64 v52, v[80:81] offset:26112
	ds_write_b64 v53, v[82:83] offset:26112
	v_mul_u32_u24_e32 v52, 0x88, v222
	v_lshlrev_b32_e32 v52, 1, v52
	v_add_u32_e32 v53, 0, v52
	v_add3_u32 v232, s1, v52, v3
	v_add3_u32 v231, v53, v54, v3
	v_mov_b32_e32 v2, v1
	v_mov_b32_e32 v3, v1
	v_lshlrev_b32_e32 v185, 2, v0
	v_mov_b32_e32 v0, v1
	v_mov_b32_e32 v192, 0xf149f2ca
	v_mov_b32_e32 v190, 0
	v_mov_b64_e32 v[58:59], v[2:3]
	v_mov_b64_e32 v[62:63], v[2:3]
	v_mov_b64_e32 v[66:67], v[2:3]
	v_mov_b64_e32 v[70:71], v[2:3]
	v_mov_b64_e32 v[74:75], v[2:3]
	v_mov_b64_e32 v[78:79], v[2:3]
	v_mov_b64_e32 v[82:83], v[2:3]
	v_mov_b64_e32 v[86:87], v[2:3]
	v_mov_b64_e32 v[106:107], v[2:3]
	v_mov_b64_e32 v[90:91], v[2:3]
	v_mov_b64_e32 v[110:111], v[2:3]
	v_mov_b64_e32 v[94:95], v[2:3]
	v_mov_b64_e32 v[114:115], v[2:3]
	v_mov_b64_e32 v[98:99], v[2:3]
	v_mov_b64_e32 v[102:103], v[2:3]
	v_mov_b64_e32 v[54:55], v[2:3]
	v_mov_b32_e32 v217, 0x3e38aa3b
	v_mov_b32_e32 v180, 0x42000000
	s_mov_b32 s77, 0
	v_xor_b32_e32 v229, 64, v185
	v_xor_b32_e32 v228, 0x80, v185
	v_or_b32_e32 v233, 16, v184
	v_or_b32_e32 v227, 4, v182
	v_or_b32_e32 v189, 8, v182
	v_or_b32_e32 v187, 12, v182
	s_sub_i32 s82, 0x41, s0
	v_mov_b32_e32 v234, v183
	v_mov_b64_e32 v[56:57], v[0:1]
	v_mov_b64_e32 v[60:61], v[0:1]
	v_mov_b64_e32 v[64:65], v[0:1]
	v_mov_b64_e32 v[68:69], v[0:1]
	v_mov_b64_e32 v[72:73], v[0:1]
	v_mov_b64_e32 v[76:77], v[0:1]
	v_mov_b64_e32 v[80:81], v[0:1]
	v_mov_b64_e32 v[84:85], v[0:1]
	v_mov_b64_e32 v[104:105], v[0:1]
	v_mov_b64_e32 v[88:89], v[0:1]
	v_mov_b64_e32 v[108:109], v[0:1]
	v_mov_b64_e32 v[92:93], v[0:1]
	v_mov_b64_e32 v[112:113], v[0:1]
	v_mov_b64_e32 v[96:97], v[0:1]
	v_mov_b64_e32 v[100:101], v[0:1]
	v_mov_b64_e32 v[52:53], v[0:1]
	v_mov_b32_e32 v191, v190
	v_mov_b32_e32 v193, v192
	s_waitcnt lgkmcnt(0)
	s_barrier
	s_branch .LBB0_708
.LBB0_707:
	v_exp_f32_e32 v199, v176
	v_exp_f32_e32 v203, v177
	v_exp_f32_e32 v195, v178
	v_exp_f32_e32 v197, v179
	v_exp_f32_e32 v201, v172
	v_exp_f32_e32 v177, v173
	v_exp_f32_e32 v179, v174
	v_exp_f32_e32 v173, v175
	v_exp_f32_e32 v175, v160
	v_exp_f32_e32 v161, v161
	v_exp_f32_e32 v198, v168
	v_exp_f32_e32 v202, v169
	v_exp_f32_e32 v194, v170
	v_exp_f32_e32 v196, v171
	v_exp_f32_e32 v200, v164
	v_exp_f32_e32 v176, v165
	v_exp_f32_e32 v178, v166
	v_exp_f32_e32 v172, v167
	v_lshl_add_u32 v0, s67, 1, v232
	v_cvt_pk_bf16_f32 v236, v199, v203
	v_cvt_pk_bf16_f32 v237, v195, v197
	v_cvt_pk_bf16_f32 v238, v201, v177
	v_cvt_pk_bf16_f32 v239, v179, v173
	ds_read_b128 v[164:167], v0
	v_cvt_pk_bf16_f32 v240, v198, v202
	v_cvt_pk_bf16_f32 v241, v194, v196
	v_cvt_pk_bf16_f32 v242, v200, v176
	v_cvt_pk_bf16_f32 v243, v178, v172
	ds_read_b128 v[244:247], v0 offset:8704
	ds_read_b128 v[248:251], v0 offset:13056
	s_waitcnt lgkmcnt(2)
	v_mfma_f32_16x16x32_bf16 v[100:103], v[236:239], v[164:167], v[100:103]
	v_exp_f32_e32 v174, v152
	v_mfma_f32_16x16x32_bf16 v[80:83], v[240:243], v[164:167], v[80:83]
	v_exp_f32_e32 v165, v162
	v_exp_f32_e32 v163, v163
	v_exp_f32_e32 v160, v153
	ds_read_b128 v[168:171], v0 offset:4352
	s_waitcnt lgkmcnt(2)
	v_mfma_f32_16x16x32_bf16 v[112:115], v[236:239], v[244:247], v[112:115]
	v_exp_f32_e32 v164, v154
	v_mfma_f32_16x16x32_bf16 v[72:75], v[240:243], v[244:247], v[72:75]
	ds_read_b128 v[244:247], v0 offset:17408
	v_exp_f32_e32 v162, v155
	ds_read_b128 v[152:155], v0 offset:26112
	s_waitcnt lgkmcnt(3)
	v_mfma_f32_16x16x32_bf16 v[92:95], v[236:239], v[248:251], v[92:95]
	v_exp_f32_e32 v167, v156
	v_mfma_f32_16x16x32_bf16 v[68:71], v[240:243], v[248:251], v[68:71]
	ds_read_b128 v[248:251], v0 offset:21760
	v_exp_f32_e32 v157, v157
	s_waitcnt lgkmcnt(3)
	v_mfma_f32_16x16x32_bf16 v[96:99], v[236:239], v[168:171], v[96:99]
	v_exp_f32_e32 v166, v148
	v_mfma_f32_16x16x32_bf16 v[76:79], v[240:243], v[168:171], v[76:79]
	v_exp_f32_e32 v169, v158
	v_exp_f32_e32 v159, v159
	s_waitcnt lgkmcnt(2)
	v_mfma_f32_16x16x32_bf16 v[108:111], v[236:239], v[244:247], v[108:111]
	v_exp_f32_e32 v168, v150
	ds_read_b128 v[208:211], v0 offset:17472
	v_mfma_f32_16x16x32_bf16 v[64:67], v[240:243], v[244:247], v[64:67]
	v_exp_f32_e32 v171, v128
	s_waitcnt lgkmcnt(1)
	v_mfma_f32_16x16x32_bf16 v[244:247], v[240:243], v[248:251], v[60:63]
	v_exp_f32_e32 v221, v129
	v_exp_f32_e32 v156, v149
	v_mfma_f32_16x16x32_bf16 v[104:107], v[236:239], v[152:155], v[104:107]
	ds_read_b128 v[60:63], v0 offset:30464
	v_exp_f32_e32 v170, v120
	v_mfma_f32_16x16x32_bf16 v[152:155], v[240:243], v[152:155], v[56:59]
	v_exp_f32_e32 v220, v121
	v_exp_f32_e32 v158, v151
	v_mfma_f32_16x16x32_bf16 v[88:91], v[236:239], v[248:251], v[88:91]
	ds_read_b128 v[56:59], v0 offset:64
	v_cvt_pk_bf16_f32 v248, v174, v160
	v_cvt_pk_bf16_f32 v249, v164, v162
	s_waitcnt lgkmcnt(1)
	v_mfma_f32_16x16x32_bf16 v[148:151], v[236:239], v[60:63], v[84:87]
	v_cvt_pk_bf16_f32 v236, v175, v161
	v_cvt_pk_bf16_f32 v237, v165, v163
	v_cvt_pk_bf16_f32 v238, v167, v157
	v_cvt_pk_bf16_f32 v239, v169, v159
	v_cvt_pk_bf16_f32 v250, v166, v156
	v_cvt_pk_bf16_f32 v251, v168, v158
	s_waitcnt lgkmcnt(0)
	v_mfma_f32_16x16x32_bf16 v[100:103], v[236:239], v[56:59], v[100:103]
	ds_read_b128 v[84:87], v0 offset:8768
	v_mfma_f32_16x16x32_bf16 v[80:83], v[248:251], v[56:59], v[80:83]
	ds_read_b128 v[56:59], v0 offset:4416
	v_mfma_f32_16x16x32_bf16 v[240:243], v[240:243], v[60:63], v[52:55]
	v_exp_f32_e32 v60, v133
	s_nop 1
	v_exp_f32_e32 v53, v144
	v_exp_f32_e32 v55, v145
	s_waitcnt lgkmcnt(0)
; #define MFMA(a, b, c) __builtin_amdgcn_mfma_f32_16x16x32_bf16(a, b, c, 0, 0, 0)
; DEV float shfl_l(float v, int srclane) { return __int_as_float(__builtin_amdgcn_ds_bpermute(srclane << 2, __float_as_int(v))); }
; DEV float ex2(float x) { return __builtin_amdgcn_exp2f(x); }
; DEV void attn_item(const Params& p, int layer, int h, int qb, float lam, bf16_t* lds) {
;     ...
; #pragma unroll
;       for (int j = 0; j < 8; j++)
; #pragma unroll
;         for (int r = 0; r < 4; r++) { const float pv = ex2(s[i][j][r] - mnew); s[i][j][r] = pv; ps += pv; }
;       if (i == 0) { mrun0 = mnew; lrun0 = lrun0 * al[0] + ps; } else { mrun1 = mnew; lrun1 = lrun1 * al[1] + ps; }
;     }
;     if (__builtin_amdgcn_ballot_w64(al[0] != 1.f || al[1] != 1.f) != 0ull) {
; #pragma unroll
;       for (int i = 0; i < 2; i++) {
;         float ao[4];
; #pragma unroll
;         for (int r = 0; r < 4; r++) ao[r] = shfl_l(al[i], lg * 4 + r);
; #pragma unroll
;         for (int je = 0; je < 8; je++)
; #pragma unroll
;           for (int r = 0; r < 4; r++) o[i][je][r] *= ao[r];
;       }
;     }
; #pragma unroll
;     for (int ks = 0; ks < 4; ks++) {
;       union { u32x4 u; bf16x8 v; } pf0, pf1;
;       pf0.u[0] = pack2(s[0][2 * ks][0], s[0][2 * ks][1]);
;       pf0.u[1] = pack2(s[0][2 * ks][2], s[0][2 * ks][3]);
;       pf0.u[2] = pack2(s[0][2 * ks + 1][0], s[0][2 * ks + 1][1]);
;       pf0.u[3] = pack2(s[0][2 * ks + 1][2], s[0][2 * ks + 1][3]);
;       pf1.u[0] = pack2(s[1][2 * ks][0], s[1][2 * ks][1]);
;       pf1.u[1] = pack2(s[1][2 * ks][2], s[1][2 * ks][3]);
;       pf1.u[2] = pack2(s[1][2 * ks + 1][0], s[1][2 * ks + 1][1]);
;       pf1.u[3] = pack2(s[1][2 * ks + 1][2], s[1][2 * ks + 1][3]);
; #pragma unroll
;       for (int je = 0; je < 8; je++) {
;         const bf16_t* vp = vq + je * 16 * PS + ks * 32;
;         union { uint2 u[2]; bf16x8 v; } vf;
;         vf.u[0] = *(const uint2*)vp;
;         vf.u[1] = *(const uint2*)(vp + 16);
;         o[0][je] = MFMA(pf0.v, vf.v, o[0][je]);
;         o[1][je] = MFMA(pf1.v, vf.v, o[1][je]);
;       }
;     }
	v_mfma_f32_16x16x32_bf16 v[96:99], v[236:239], v[56:59], v[96:99]
	v_exp_f32_e32 v54, v137
	v_mfma_f32_16x16x32_bf16 v[76:79], v[248:251], v[56:59], v[76:79]
	v_exp_f32_e32 v57, v146
	v_mov_b32_e32 v52, v147
	ds_read_b128 v[144:147], v0 offset:13120
	v_exp_f32_e32 v63, v52
	v_exp_f32_e32 v59, v140
	v_exp_f32_e32 v61, v141
	v_mfma_f32_16x16x32_bf16 v[112:115], v[236:239], v[84:87], v[112:115]
	v_mov_b32_e32 v56, v138
	v_exp_f32_e32 v62, v139
	v_mfma_f32_16x16x32_bf16 v[72:75], v[248:251], v[84:87], v[72:75]
	v_exp_f32_e32 v85, v142
	v_exp_f32_e32 v87, v143
	s_waitcnt lgkmcnt(0)
	v_mfma_f32_16x16x32_bf16 v[92:95], v[236:239], v[144:147], v[92:95]
	v_mov_b32_e32 v52, v136
	ds_read_b128 v[140:143], v0 offset:21824
	ds_read_b128 v[136:139], v0 offset:26176
	v_mfma_f32_16x16x32_bf16 v[68:71], v[248:251], v[144:147], v[68:71]
	ds_read_b128 v[144:147], v0 offset:30528
	v_exp_f32_e32 v52, v52
	v_exp_f32_e32 v56, v56
	v_exp_f32_e32 v58, v132
	v_exp_f32_e32 v84, v134
	v_exp_f32_e32 v86, v135
	v_mfma_f32_16x16x32_bf16 v[108:111], v[236:239], v[208:211], v[108:111]
	v_mfma_f32_16x16x32_bf16 v[64:67], v[248:251], v[208:211], v[64:67]
	v_cvt_pk_bf16_f32 v208, v52, v54
	v_cvt_pk_bf16_f32 v209, v56, v62
	v_cvt_pk_bf16_f32 v210, v58, v60
	s_waitcnt lgkmcnt(2)
	v_mfma_f32_16x16x32_bf16 v[88:91], v[236:239], v[140:143], v[88:91]
	v_cvt_pk_bf16_f32 v211, v84, v86
	s_waitcnt lgkmcnt(1)
	v_mfma_f32_16x16x32_bf16 v[104:107], v[236:239], v[136:139], v[104:107]
	s_waitcnt lgkmcnt(0)
	v_mfma_f32_16x16x32_bf16 v[132:135], v[236:239], v[144:147], v[148:151]
	ds_read_b128 v[236:239], v0 offset:8832
	s_nop 1
	v_cvt_pk_bf16_f32 v148, v53, v55
	v_cvt_pk_bf16_f32 v149, v57, v63
	v_cvt_pk_bf16_f32 v150, v59, v61
	v_cvt_pk_bf16_f32 v151, v85, v87
	v_mfma_f32_16x16x32_bf16 v[144:147], v[248:251], v[144:147], v[240:243]
	s_nop 2
	v_exp_f32_e32 v241, v130
	v_exp_f32_e32 v243, v131
	ds_read_b128 v[128:131], v0 offset:13184
	s_waitcnt lgkmcnt(1)
	v_mfma_f32_16x16x32_bf16 v[112:115], v[148:151], v[236:239], v[112:115]
	v_exp_f32_e32 v240, v122
	v_exp_f32_e32 v242, v123
	v_mfma_f32_16x16x32_bf16 v[72:75], v[208:211], v[236:239], v[72:75]
	v_exp_f32_e32 v237, v124
	v_exp_f32_e32 v239, v125
	v_exp_f32_e32 v236, v116
	v_mfma_f32_16x16x32_bf16 v[140:143], v[248:251], v[140:143], v[244:247]
	v_exp_f32_e32 v238, v117
	ds_read_b128 v[120:123], v0 offset:26240
	v_mfma_f32_16x16x32_bf16 v[136:139], v[248:251], v[136:139], v[152:155]
	v_exp_f32_e32 v245, v126
	v_exp_f32_e32 v247, v127
	ds_read_b128 v[152:155], v0 offset:128
	s_waitcnt lgkmcnt(2)
	v_mfma_f32_16x16x32_bf16 v[92:95], v[148:151], v[128:131], v[92:95]
	ds_read_b128 v[124:127], v0 offset:21888
	v_exp_f32_e32 v244, v118
	v_mfma_f32_16x16x32_bf16 v[68:71], v[208:211], v[128:131], v[68:71]
	ds_read_b128 v[128:131], v0 offset:30592
	v_exp_f32_e32 v246, v119
	s_waitcnt lgkmcnt(2)
	v_mfma_f32_16x16x32_bf16 v[100:103], v[148:151], v[152:155], v[100:103]
	v_mfma_f32_16x16x32_bf16 v[80:83], v[208:211], v[152:155], v[80:83]
	ds_read_b128 v[152:155], v0 offset:4480
	s_waitcnt lgkmcnt(2)
	v_mfma_f32_16x16x32_bf16 v[88:91], v[148:151], v[124:127], v[88:91]
	v_mfma_f32_16x16x32_bf16 v[124:127], v[208:211], v[124:127], v[140:143]
	v_mfma_f32_16x16x32_bf16 v[104:107], v[148:151], v[120:123], v[104:107]
	s_nop 1
	v_cvt_pk_bf16_f32 v140, v170, v220
	v_cvt_pk_bf16_f32 v141, v240, v242
	v_cvt_pk_bf16_f32 v142, v236, v238
	v_mfma_f32_16x16x32_bf16 v[120:123], v[208:211], v[120:123], v[136:139]
	v_cvt_pk_bf16_f32 v143, v244, v246
	s_waitcnt lgkmcnt(1)
	v_mfma_f32_16x16x32_bf16 v[116:119], v[148:151], v[128:131], v[132:135]
	ds_read_b128 v[136:139], v0 offset:192
	s_nop 1
	v_cvt_pk_bf16_f32 v132, v171, v221
	v_cvt_pk_bf16_f32 v133, v241, v243
	v_cvt_pk_bf16_f32 v134, v237, v239
	v_cvt_pk_bf16_f32 v135, v245, v247
	s_waitcnt lgkmcnt(1)
	v_mfma_f32_16x16x32_bf16 v[96:99], v[148:151], v[152:155], v[96:99]
	v_mfma_f32_16x16x32_bf16 v[76:79], v[208:211], v[152:155], v[76:79]
	ds_read_b128 v[152:155], v0 offset:17536
	s_waitcnt lgkmcnt(1)
	v_mfma_f32_16x16x32_bf16 v[100:103], v[132:135], v[136:139], v[100:103]
	v_mfma_f32_16x16x32_bf16 v[80:83], v[140:143], v[136:139], v[80:83]
	ds_read_b128 v[136:139], v0 offset:4544
	v_mfma_f32_16x16x32_bf16 v[128:131], v[208:211], v[128:131], v[144:147]
	s_nop 2
	v_add_f32_e64 v144, v198, 0
	v_add_f32_e64 v145, v199, 0
	s_waitcnt lgkmcnt(1)
	v_mfma_f32_16x16x32_bf16 v[108:111], v[148:151], v[152:155], v[108:111]
	v_add_f32_e64 v148, v202, v144
	v_add_f32_e64 v149, v203, v145
	ds_read_b128 v[144:147], v0 offset:8896
	s_waitcnt lgkmcnt(1)
	v_mfma_f32_16x16x32_bf16 v[96:99], v[132:135], v[136:139], v[96:99]
	v_mfma_f32_16x16x32_bf16 v[76:79], v[140:143], v[136:139], v[76:79]
	v_add_f32_e64 v136, v194, v148
	v_add_f32_e64 v137, v195, v149
	v_pk_add_f32 v[136:137], v[196:197], v[136:137]
	s_waitcnt lgkmcnt(0)
	v_mfma_f32_16x16x32_bf16 v[112:115], v[132:135], v[144:147], v[112:115]
	v_add_f32_e64 v136, v200, v136
	v_add_f32_e64 v137, v201, v137
	v_pk_add_f32 v[136:137], v[176:177], v[136:137]
	v_mfma_f32_16x16x32_bf16 v[72:75], v[140:143], v[144:147], v[72:75]
	v_add_f32_e64 v148, v178, v136
	v_add_f32_e64 v149, v179, v137
	ds_read_b128 v[136:139], v0 offset:13248
	v_pk_add_f32 v[144:145], v[172:173], v[148:149]
	s_waitcnt lgkmcnt(0)
	v_mfma_f32_16x16x32_bf16 v[92:95], v[132:135], v[136:139], v[92:95]
	v_add_f32_e64 v144, v174, v144
	v_add_f32_e64 v145, v175, v145
	v_pk_add_f32 v[144:145], v[160:161], v[144:145]
	v_mfma_f32_16x16x32_bf16 v[68:71], v[140:143], v[136:139], v[68:71]
	v_add_f32_e64 v144, v164, v144
	v_add_f32_e64 v145, v165, v145
	v_pk_add_f32 v[148:149], v[162:163], v[144:145]
	ds_read_b128 v[144:147], v0 offset:17600
	v_pk_add_f32 v[136:137], v[166:167], v[148:149]
	v_mfma_f32_16x16x32_bf16 v[64:67], v[208:211], v[152:155], v[64:67]
	v_add_f32_e64 v136, v156, v136
	v_add_f32_e64 v137, v157, v137
	v_pk_add_f32 v[136:137], v[168:169], v[136:137]
	s_waitcnt lgkmcnt(0)
; #define MFMA(a, b, c) __builtin_amdgcn_mfma_f32_16x16x32_bf16(a, b, c, 0, 0, 0)
; DEV void attn_item(const Params& p, int layer, int h, int qb, float lam, bf16_t* lds) {
;     ...
;   for (int kb = 0; kb <= qb; kb++) {
;     const int cur = kb & 1;
;     const bf16_t* kp = KV + cur * TS + lr * PS + grp * 64 + lg * 8;
;     const bf16_t* vq = KV + 2 * TS + cur * TS + lr * PS + lg * 4;
;     {
;       bf16_t* sp = KV + (cur ^ 1) * TS + lrow * PS + lc8;
;       ASTORE(sp)
;     }
;     __builtin_amdgcn_sched_barrier(0);
;     f32x4 s[2][8];
;     {
; #pragma unroll
;       for (int j = 0; j < 8; j++) {
;         const bf16x8 kf0 = *(const bf16x8*)(kp + j * 16 * PS);
;         const bf16x8 kf1 = *(const bf16x8*)(kp + j * 16 * PS + 32);
;         s[0][j] = MFMA(kf0, a00, ((f32x4){0.f, 0.f, 0.f, 0.f}));
;         s[1][j] = MFMA(kf0, a10, ((f32x4){0.f, 0.f, 0.f, 0.f}));
;         s[0][j] = MFMA(kf1, a01, s[0][j]);
;         s[1][j] = MFMA(kf1, a11, s[1][j]);
;       }
	v_mfma_f32_16x16x32_bf16 v[108:111], v[132:135], v[144:147], v[108:111]
	v_add_f32_e64 v136, v158, v136
	v_add_f32_e64 v137, v159, v137
	v_pk_add_f32 v[52:53], v[52:53], v[136:137]
	ds_read_b128 v[136:139], v0 offset:21952
	v_pk_add_f32 v[52:53], v[54:55], v[52:53]
	v_mfma_f32_16x16x32_bf16 v[64:67], v[140:143], v[144:147], v[64:67]
	v_add_f32_e64 v52, v56, v52
	v_add_f32_e64 v53, v57, v53
	v_pk_add_f32 v[52:53], v[62:63], v[52:53]
	s_waitcnt lgkmcnt(0)
	v_mfma_f32_16x16x32_bf16 v[88:91], v[132:135], v[136:139], v[88:91]
	v_add_f32_e64 v52, v58, v52
	v_add_f32_e64 v53, v59, v53
	v_pk_add_f32 v[56:57], v[60:61], v[52:53]
	ds_read_b128 v[52:55], v0 offset:26304
	v_pk_add_f32 v[56:57], v[84:85], v[56:57]
	v_mfma_f32_16x16x32_bf16 v[60:63], v[140:143], v[136:139], v[124:127]
	v_add_f32_e64 v56, v86, v56
	v_add_f32_e64 v57, v87, v57
	v_pk_add_f32 v[56:57], v[170:171], v[56:57]
	s_waitcnt lgkmcnt(0)
	v_mfma_f32_16x16x32_bf16 v[104:107], v[132:135], v[52:55], v[104:107]
	v_add_f32_e64 v56, v220, v56
	v_add_f32_e64 v57, v221, v57
	ds_read_b128 v[124:127], v0 offset:30656
	v_pk_add_f32 v[84:85], v[240:241], v[56:57]
	v_mfma_f32_16x16x32_bf16 v[56:59], v[140:143], v[52:55], v[120:123]
	v_add_f32_e64 v52, v242, v84
	v_add_f32_e64 v53, v243, v85
	v_pk_add_f32 v[52:53], v[236:237], v[52:53]
	s_waitcnt lgkmcnt(0)
	v_mfma_f32_16x16x32_bf16 v[84:87], v[132:135], v[124:127], v[116:119]
	v_add_f32_e64 v52, v238, v52
	v_add_f32_e64 v53, v239, v53
	v_pk_add_f32 v[52:53], v[244:245], v[52:53]
	s_nop 0
	v_pk_add_f32 v[52:53], v[246:247], v[52:53]
	s_nop 0
	v_pk_fma_f32 v[190:191], v[190:191], v[2:3], v[52:53]
	v_mfma_f32_16x16x32_bf16 v[52:55], v[140:143], v[124:127], v[128:131]
	s_add_i32 s77, s77, 1
	s_cmp_eq_u32 s82, s77
	v_add_u32_e32 v234, 0x80, v234
	s_barrier
	s_cbranch_scc1 .LBB0_712
.LBB0_708:
	s_and_b32 s0, s77, 1
	s_mul_i32 s67, s0, 0x4400
	s_xor_b32 s0, s0, 1
	s_mul_i32 s0, s0, 0x8800
	v_add_u32_e32 v2, s0, v230
	s_waitcnt vmcnt(7)
	ds_write_b128 v2, v[20:23]
	s_waitcnt vmcnt(6)
	ds_write_b128 v2, v[24:27] offset:8704
	s_waitcnt vmcnt(5)
	ds_write_b128 v2, v[28:31] offset:17408
	s_waitcnt vmcnt(4)
	ds_write_b128 v2, v[32:35] offset:26112
	v_add_u32_e32 v3, s0, v204
	v_add_u32_e32 v25, s0, v205
	s_nop 0
	s_waitcnt vmcnt(3)
	ds_write_b64 v3, v[36:37]
	ds_write_b64 v25, v[38:39]
	s_waitcnt vmcnt(2)
	ds_write_b64 v3, v[40:41] offset:8704
	ds_write_b64 v25, v[42:43] offset:8704
	v_lshl_add_u32 v0, s67, 1, v231
	s_waitcnt vmcnt(1)
	ds_write_b64 v3, v[44:45] offset:17408
	ds_write_b64 v25, v[46:47] offset:17408
	s_waitcnt vmcnt(0)
	ds_write_b64 v3, v[48:49] offset:26112
	ds_write_b64 v25, v[50:51] offset:26112
	v_cmp_neq_f32_e64 s[98:99], s68, v193
	v_cmp_neq_f32_e32 vcc, s68, v192
	s_nop 0
	v_cndmask_b32_e64 v206, 0, v193, s[98:99]
	v_cndmask_b32_e32 v212, 0, v192, vcc
	v_xor_b32_e32 v28, 0x80000000, v206
	v_xor_b32_e32 v48, 0x80000000, v212
	v_mov_b32_e32 v29, v28
	v_mov_b32_e32 v30, v28
	v_mov_b32_e32 v31, v28
	v_mov_b32_e32 v49, v48
	v_mov_b32_e32 v50, v48
	v_mov_b32_e32 v51, v48
	ds_read_b128 v[20:23], v0
	ds_read_b128 v[24:27], v0 offset:64
	ds_read_b128 v[32:35], v0 offset:4352
	ds_read_b128 v[36:39], v0 offset:4416
	ds_read_b128 v[40:43], v0 offset:8704
	ds_read_b128 v[44:47], v0 offset:8768
	s_waitcnt lgkmcnt(4)
	v_mfma_f32_16x16x32_bf16 v[176:179], v[20:23], v[4:7], v[28:31]
	v_mfma_f32_16x16x32_bf16 v[168:171], v[20:23], v[12:15], v[48:51]
	v_mfma_f32_16x16x32_bf16 v[176:179], v[24:27], v[8:11], v[176:179]
	v_mfma_f32_16x16x32_bf16 v[168:171], v[24:27], v[16:19], v[168:171]
	ds_read_b128 v[20:23], v0 offset:13056
	ds_read_b128 v[24:27], v0 offset:13120
	s_waitcnt lgkmcnt(4)
	v_mfma_f32_16x16x32_bf16 v[172:175], v[32:35], v[4:7], v[28:31]
	v_mfma_f32_16x16x32_bf16 v[164:167], v[32:35], v[12:15], v[48:51]
	v_mfma_f32_16x16x32_bf16 v[172:175], v[36:39], v[8:11], v[172:175]
	v_mfma_f32_16x16x32_bf16 v[164:167], v[36:39], v[16:19], v[164:167]
	ds_read_b128 v[32:35], v0 offset:17408
	ds_read_b128 v[36:39], v0 offset:17472
	s_waitcnt lgkmcnt(4)
	v_mfma_f32_16x16x32_bf16 v[160:163], v[40:43], v[4:7], v[28:31]
	v_mfma_f32_16x16x32_bf16 v[152:155], v[40:43], v[12:15], v[48:51]
	v_mfma_f32_16x16x32_bf16 v[160:163], v[44:47], v[8:11], v[160:163]
	v_mfma_f32_16x16x32_bf16 v[152:155], v[44:47], v[16:19], v[152:155]
	ds_read_b128 v[40:43], v0 offset:21760
	ds_read_b128 v[44:47], v0 offset:21824
	s_waitcnt lgkmcnt(4)
	v_mfma_f32_16x16x32_bf16 v[156:159], v[20:23], v[4:7], v[28:31]
	v_mfma_f32_16x16x32_bf16 v[148:151], v[20:23], v[12:15], v[48:51]
	v_mfma_f32_16x16x32_bf16 v[156:159], v[24:27], v[8:11], v[156:159]
	v_mfma_f32_16x16x32_bf16 v[148:151], v[24:27], v[16:19], v[148:151]
	ds_read_b128 v[20:23], v0 offset:26112
	ds_read_b128 v[24:27], v0 offset:26176
	s_waitcnt lgkmcnt(4)
	v_mfma_f32_16x16x32_bf16 v[144:147], v[32:35], v[4:7], v[28:31]
	v_mfma_f32_16x16x32_bf16 v[136:139], v[32:35], v[12:15], v[48:51]
	v_mfma_f32_16x16x32_bf16 v[144:147], v[36:39], v[8:11], v[144:147]
	v_mfma_f32_16x16x32_bf16 v[136:139], v[36:39], v[16:19], v[136:139]
	ds_read_b128 v[32:35], v0 offset:30464
	ds_read_b128 v[36:39], v0 offset:30528
	s_waitcnt lgkmcnt(4)
	v_mfma_f32_16x16x32_bf16 v[140:143], v[40:43], v[4:7], v[28:31]
	v_mfma_f32_16x16x32_bf16 v[132:135], v[40:43], v[12:15], v[48:51]
	v_mfma_f32_16x16x32_bf16 v[140:143], v[44:47], v[8:11], v[140:143]
	v_mfma_f32_16x16x32_bf16 v[132:135], v[44:47], v[16:19], v[132:135]
	s_waitcnt lgkmcnt(2)
	v_mfma_f32_16x16x32_bf16 v[128:131], v[20:23], v[4:7], v[28:31]
	v_mfma_f32_16x16x32_bf16 v[120:123], v[20:23], v[12:15], v[48:51]
	v_mfma_f32_16x16x32_bf16 v[128:131], v[24:27], v[8:11], v[128:131]
	v_mfma_f32_16x16x32_bf16 v[120:123], v[24:27], v[16:19], v[120:123]
	s_waitcnt lgkmcnt(0)
; #define MFMA(a, b, c) __builtin_amdgcn_mfma_f32_16x16x32_bf16(a, b, c, 0, 0, 0)
; DEV void attn_item(const Params& p, int layer, int h, int qb, float lam, bf16_t* lds) {
;     ...
;     __builtin_amdgcn_sched_barrier(0);
;     f32x4 s[2][8];
;     {
; #pragma unroll
;       for (int j = 0; j < 8; j++) {
;         const bf16x8 kf0 = *(const bf16x8*)(kp + j * 16 * PS);
;         const bf16x8 kf1 = *(const bf16x8*)(kp + j * 16 * PS + 32);
;         s[0][j] = MFMA(kf0, a00, ((f32x4){0.f, 0.f, 0.f, 0.f}));
;         s[1][j] = MFMA(kf0, a10, ((f32x4){0.f, 0.f, 0.f, 0.f}));
;         s[0][j] = MFMA(kf1, a01, s[0][j]);
;         s[1][j] = MFMA(kf1, a11, s[1][j]);
;       }
;     }
;     __builtin_amdgcn_sched_barrier(0);
;     {
;       const int kbn = (kb + 2 <= qb) ? kb + 2 : qb;
;       ALOAD(kbn)
;     }
;     __builtin_amdgcn_sched_barrier(0);
;     if (kb == qb || kb == 0) {
; #pragma unroll
;       for (int i = 0; i < 2; i++)
; #pragma unroll
;         for (int j = 0; j < 8; j++)
; #pragma unroll
;           for (int r = 0; r < 4; r++) {
;             const int key = kb * 128 + j * 16 + lg * 4 + r;
;             if (key > qrow0 + 16 * i || key < 112) s[i][j][r] = -1e30f;
	v_mfma_f32_16x16x32_bf16 v[124:127], v[32:35], v[4:7], v[28:31]
	v_mfma_f32_16x16x32_bf16 v[116:119], v[32:35], v[12:15], v[48:51]
	v_mfma_f32_16x16x32_bf16 v[124:127], v[36:39], v[8:11], v[124:127]
	v_mfma_f32_16x16x32_bf16 v[116:119], v[36:39], v[16:19], v[116:119]
	s_nop 0
	s_add_i32 s0, s77, 2
	s_min_u32 s0, s0, s76
	v_lshl_add_u32 v0, s0, 17, v186
	s_nop 1
	v_add_u32_e32 v20, 0x8000, v0
	v_mov_b32_e32 v21, v1
	v_lshl_add_u64 v[2:3], v[0:1], 1, s[78:79]
	v_lshl_add_u64 v[24:25], v[20:21], 1, s[78:79]
	global_load_dwordx4 v[20:23], v[2:3], off
	s_nop 0
	global_load_dwordx4 v[24:27], v[24:25], off
	v_add_u32_e32 v2, 0x10000, v0
	v_add_u32_e32 v0, 0x18000, v0
	v_mov_b32_e32 v3, v1
	v_lshl_add_u64 v[32:33], v[0:1], 1, s[78:79]
	v_lshl_add_u32 v0, s0, 7, v188
	v_lshl_add_u64 v[2:3], v[2:3], 1, s[78:79]
	v_add_u32_e32 v36, 0x41000, v0
	v_mov_b32_e32 v37, v1
	global_load_dwordx4 v[28:31], v[2:3], off
	s_nop 0
	global_load_dwordx4 v[32:35], v[32:33], off
	v_lshl_add_u64 v[2:3], v[0:1], 1, s[70:71]
	v_lshl_add_u64 v[40:41], v[36:37], 1, s[70:71]
	global_load_dwordx4 v[36:39], v[2:3], off
	s_nop 0
	global_load_dwordx4 v[40:43], v[40:41], off
	v_add_u32_e32 v2, 0x82000, v0
	v_mov_b32_e32 v3, v1
	v_add_u32_e32 v0, 0xc3000, v0
	v_lshl_add_u64 v[2:3], v[2:3], 1, s[70:71]
	v_lshl_add_u64 v[48:49], v[0:1], 1, s[70:71]
	global_load_dwordx4 v[44:47], v[2:3], off
	s_nop 0
	global_load_dwordx4 v[48:51], v[48:49], off
	s_cmp_lg_u32 s76, s77
	s_cselect_b64 s[0:1], -1, 0
	s_cmp_eq_u32 s77, 0
	s_cselect_b64 s[2:3], -1, 0
	s_cmp_lg_u32 s77, 0
	s_cselect_b64 s[6:7], -1, 0
	s_and_b64 s[0:1], s[0:1], s[6:7]
	s_and_b64 vcc, exec, s[0:1]
	s_cbranch_vccnz .LBB0_710
	v_cmp_gt_u32_e32 vcc, v234, v184
	v_mov_b32_e32 v0, s68
	s_or_b64 s[0:1], s[2:3], vcc
	v_cndmask_b32_e64 v176, v176, v0, s[0:1]
	v_cmp_ge_u32_e64 s[0:1], v234, v184
	s_or_b64 s[0:1], s[2:3], s[0:1]
	v_add_u32_e32 v2, 2, v234
	v_cndmask_b32_e64 v177, v177, v219, s[0:1]
	v_cmp_gt_u32_e64 s[0:1], v2, v184
	s_or_b64 s[0:1], s[2:3], s[0:1]
	v_add_u32_e32 v3, 3, v234
	v_cndmask_b32_e64 v178, v178, v219, s[0:1]
	v_cmp_gt_u32_e64 s[0:1], v3, v184
	s_or_b64 s[0:1], s[2:3], s[0:1]
	v_add_u32_e32 v0, 16, v234
	v_cndmask_b32_e64 v179, v179, v219, s[0:1]
	v_cmp_gt_u32_e64 s[0:1], v0, v184
	v_cmp_gt_u32_e64 s[6:7], s61, v0
	v_mov_b32_e32 v0, s68
	s_or_b64 s[0:1], s[0:1], s[6:7]
	v_add_u32_e32 v194, 17, v234
	v_cndmask_b32_e64 v172, v172, v0, s[0:1]
	v_cmp_gt_u32_e64 s[0:1], v194, v184
	v_cmp_gt_u32_e64 s[8:9], s61, v194
	s_or_b64 s[0:1], s[0:1], s[8:9]
	v_add_u32_e32 v195, 18, v234
	v_cndmask_b32_e64 v173, v173, v219, s[0:1]
	v_cmp_gt_u32_e64 s[0:1], v195, v184
	v_cmp_gt_u32_e64 s[10:11], s61, v195
	s_or_b64 s[0:1], s[0:1], s[10:11]
	v_add_u32_e32 v196, 19, v234
	v_cndmask_b32_e64 v174, v174, v219, s[0:1]
	v_cmp_gt_u32_e64 s[0:1], v196, v184
	v_cmp_gt_u32_e64 s[12:13], s61, v196
	s_or_b64 s[0:1], s[0:1], s[12:13]
	v_add_u32_e32 v197, 32, v234
	v_cndmask_b32_e64 v175, v175, v219, s[0:1]
	v_cmp_gt_u32_e64 s[0:1], v197, v184
	v_cmp_gt_u32_e64 s[14:15], s61, v197
	s_or_b64 s[0:1], s[0:1], s[14:15]
	v_add_u32_e32 v198, 33, v234
	s_or_b64 vcc, vcc, s[6:7]
	v_cndmask_b32_e64 v160, v160, v0, s[0:1]
	v_cmp_gt_u32_e64 s[0:1], v198, v184
	v_cmp_gt_u32_e64 s[16:17], s61, v198
	v_cndmask_b32_e32 v164, v164, v0, vcc
	v_cmp_gt_u32_e32 vcc, v194, v233
	s_or_b64 s[0:1], s[0:1], s[16:17]
	v_add_u32_e32 v199, 34, v234
	s_or_b64 vcc, vcc, s[8:9]
	v_cndmask_b32_e64 v161, v161, v219, s[0:1]
	v_cmp_gt_u32_e64 s[0:1], v199, v184
	v_cmp_gt_u32_e64 s[18:19], s61, v199
	v_cndmask_b32_e32 v165, v165, v219, vcc
	v_cmp_gt_u32_e32 vcc, v195, v233
	s_or_b64 s[0:1], s[0:1], s[18:19]
	v_add_u32_e32 v200, 35, v234
	s_or_b64 vcc, vcc, s[10:11]
	v_cndmask_b32_e64 v162, v162, v219, s[0:1]
	v_cmp_gt_u32_e64 s[0:1], v200, v184
	v_cmp_gt_u32_e64 s[20:21], s61, v200
	v_cndmask_b32_e32 v166, v166, v219, vcc
	v_cmp_gt_u32_e32 vcc, v196, v233
	s_or_b64 s[0:1], s[0:1], s[20:21]
	v_add_u32_e32 v201, 48, v234
	s_or_b64 vcc, vcc, s[12:13]
	v_cndmask_b32_e64 v163, v163, v219, s[0:1]
	v_cmp_gt_u32_e64 s[0:1], v201, v184
	v_cmp_gt_u32_e64 s[22:23], s61, v201
	v_cndmask_b32_e32 v167, v167, v219, vcc
	v_cmp_gt_u32_e32 vcc, v197, v233
	s_or_b64 s[0:1], s[0:1], s[22:23]
	v_add_u32_e32 v202, 49, v234
	s_or_b64 vcc, vcc, s[14:15]
	v_cndmask_b32_e64 v156, v156, v0, s[0:1]
	v_cmp_gt_u32_e64 s[0:1], v202, v184
	v_cmp_gt_u32_e64 s[24:25], s61, v202
	v_cndmask_b32_e32 v152, v152, v0, vcc
	v_cmp_gt_u32_e32 vcc, v198, v233
	s_or_b64 s[0:1], s[0:1], s[24:25]
	v_add_u32_e32 v203, 50, v234
	s_or_b64 vcc, vcc, s[16:17]
	v_cndmask_b32_e64 v157, v157, v219, s[0:1]
	v_cmp_gt_u32_e64 s[0:1], v203, v184
	v_cmp_gt_u32_e64 s[26:27], s61, v203
	v_cndmask_b32_e32 v153, v153, v219, vcc
	v_cmp_gt_u32_e32 vcc, v199, v233
	s_or_b64 s[0:1], s[0:1], s[26:27]
	v_add_u32_e32 v208, 51, v234
	s_or_b64 vcc, vcc, s[18:19]
	v_cndmask_b32_e64 v158, v158, v219, s[0:1]
	v_cmp_gt_u32_e64 s[0:1], v208, v184
	v_cmp_gt_u32_e64 s[28:29], s61, v208
	v_cndmask_b32_e32 v154, v154, v219, vcc
	v_cmp_gt_u32_e32 vcc, v200, v233
	s_or_b64 s[0:1], s[0:1], s[28:29]
	v_add_u32_e32 v209, 64, v234
	s_or_b64 vcc, vcc, s[20:21]
	v_cndmask_b32_e64 v159, v159, v219, s[0:1]
	v_cmp_gt_u32_e64 s[0:1], v209, v184
	v_cmp_gt_u32_e64 s[30:31], s61, v209
	v_cndmask_b32_e32 v155, v155, v219, vcc
	v_cmp_gt_u32_e32 vcc, v201, v233
	s_or_b64 s[0:1], s[0:1], s[30:31]
	v_add_u32_e32 v210, 0x41, v234
	s_or_b64 vcc, vcc, s[22:23]
	v_cndmask_b32_e64 v144, v144, v0, s[0:1]
	v_cmp_gt_u32_e64 s[0:1], v210, v184
	v_cmp_gt_u32_e64 s[34:35], s61, v210
	v_cndmask_b32_e32 v148, v148, v0, vcc
	v_cmp_gt_u32_e32 vcc, v202, v233
	s_or_b64 s[0:1], s[0:1], s[34:35]
; DEV void attn_item(const Params& p, int layer, int h, int qb, float lam, bf16_t* lds) {
;     ...
;     if (kb == qb || kb == 0) {
; #pragma unroll
;       for (int i = 0; i < 2; i++)
; #pragma unroll
;         for (int j = 0; j < 8; j++)
; #pragma unroll
;           for (int r = 0; r < 4; r++) {
;             const int key = kb * 128 + j * 16 + lg * 4 + r;
;             if (key > qrow0 + 16 * i || key < 112) s[i][j][r] = -1e30f;
;           }
;     }
	v_add_u32_e32 v211, 0x42, v234
	s_or_b64 vcc, vcc, s[24:25]
	v_cndmask_b32_e64 v145, v145, v219, s[0:1]
	v_cmp_gt_u32_e64 s[0:1], v211, v184
	v_cmp_gt_u32_e64 s[36:37], s61, v211
	v_cndmask_b32_e32 v149, v149, v219, vcc
	v_cmp_gt_u32_e32 vcc, v203, v233
	s_or_b64 s[0:1], s[0:1], s[36:37]
	v_add_u32_e32 v220, 0x43, v234
	s_or_b64 vcc, vcc, s[26:27]
	v_cndmask_b32_e64 v146, v146, v219, s[0:1]
	v_cmp_gt_u32_e64 s[0:1], v220, v184
	v_cmp_gt_u32_e64 s[38:39], s61, v220
	v_cndmask_b32_e32 v150, v150, v219, vcc
	v_cmp_gt_u32_e32 vcc, v208, v233
	s_or_b64 s[0:1], s[0:1], s[38:39]
	v_add_u32_e32 v221, 0x50, v234
	s_or_b64 vcc, vcc, s[28:29]
	v_cndmask_b32_e64 v147, v147, v219, s[0:1]
	v_cmp_gt_u32_e64 s[0:1], v221, v184
	v_cmp_gt_u32_e64 s[40:41], s61, v221
	v_cndmask_b32_e32 v151, v151, v219, vcc
	v_cmp_gt_u32_e32 vcc, v209, v233
	s_or_b64 s[0:1], s[0:1], s[40:41]
	v_add_u32_e32 v236, 0x51, v234
	s_or_b64 vcc, vcc, s[30:31]
	v_cndmask_b32_e64 v140, v140, v0, s[0:1]
	v_cmp_gt_u32_e64 s[0:1], v236, v184
	v_cmp_gt_u32_e64 s[42:43], s61, v236
	v_cndmask_b32_e32 v136, v136, v0, vcc
	v_cmp_gt_u32_e32 vcc, v210, v233
	s_or_b64 s[0:1], s[0:1], s[42:43]
	v_add_u32_e32 v237, 0x52, v234
	s_or_b64 vcc, vcc, s[34:35]
	v_cndmask_b32_e64 v141, v141, v219, s[0:1]
	v_cmp_gt_u32_e64 s[0:1], v237, v184
	v_cmp_gt_u32_e64 s[44:45], s61, v237
	v_cndmask_b32_e32 v137, v137, v219, vcc
	v_cmp_gt_u32_e32 vcc, v211, v233
	s_or_b64 s[0:1], s[0:1], s[44:45]
	v_add_u32_e32 v238, 0x53, v234
	s_or_b64 vcc, vcc, s[36:37]
	v_cndmask_b32_e64 v142, v142, v219, s[0:1]
	v_cmp_gt_u32_e64 s[0:1], v238, v184
	v_cmp_gt_u32_e64 s[46:47], s61, v238
	v_cndmask_b32_e32 v138, v138, v219, vcc
	v_cmp_gt_u32_e32 vcc, v220, v233
	s_or_b64 s[0:1], s[0:1], s[46:47]
	v_add_u32_e32 v239, 0x60, v234
	s_or_b64 vcc, vcc, s[38:39]
	v_cndmask_b32_e64 v143, v143, v219, s[0:1]
	v_cmp_gt_u32_e64 s[0:1], v239, v184
	v_cmp_gt_u32_e64 s[48:49], s61, v239
	v_cndmask_b32_e32 v139, v139, v219, vcc
	v_cmp_gt_u32_e32 vcc, v221, v233
	s_or_b64 s[0:1], s[0:1], s[48:49]
	v_add_u32_e32 v240, 0x61, v234
	s_or_b64 vcc, vcc, s[40:41]
	v_cndmask_b32_e64 v128, v128, v0, s[0:1]
	v_cmp_gt_u32_e64 s[52:53], v240, v184
	v_cmp_gt_u32_e64 s[0:1], s61, v240
	v_cndmask_b32_e32 v132, v132, v0, vcc
	v_cmp_gt_u32_e32 vcc, v236, v233
	s_or_b64 s[52:53], s[52:53], s[0:1]
	v_add_u32_e32 v241, 0x62, v234
	s_or_b64 vcc, vcc, s[42:43]
	v_cndmask_b32_e64 v129, v129, v219, s[52:53]
	v_cmp_gt_u32_e64 s[54:55], v241, v184
	v_cmp_gt_u32_e64 s[52:53], s61, v241
	v_cndmask_b32_e32 v133, v133, v219, vcc
	v_cmp_gt_u32_e32 vcc, v237, v233
	s_or_b64 s[54:55], s[54:55], s[52:53]
	v_add_u32_e32 v242, 0x63, v234
	s_or_b64 vcc, vcc, s[44:45]
	v_cndmask_b32_e64 v130, v130, v219, s[54:55]
	v_cmp_gt_u32_e64 s[58:59], v242, v184
	v_cmp_gt_u32_e64 s[54:55], s61, v242
	v_cndmask_b32_e32 v134, v134, v219, vcc
	v_cmp_gt_u32_e32 vcc, v238, v233
	s_or_b64 s[58:59], s[58:59], s[54:55]
	v_add_u32_e32 v243, 0x70, v234
	s_or_b64 vcc, vcc, s[46:47]
	v_cndmask_b32_e64 v131, v131, v219, s[58:59]
	v_cmp_gt_u32_e64 s[58:59], v243, v184
	v_add_u32_e32 v244, 0x71, v234
	v_cndmask_b32_e32 v135, v135, v219, vcc
	v_cmp_gt_u32_e32 vcc, v239, v233
	v_cndmask_b32_e64 v124, v124, v0, s[58:59]
	v_cmp_le_u32_e64 s[58:59], v244, v184
	v_add_u32_e32 v245, 0x72, v234
	s_or_b64 vcc, vcc, s[48:49]
	v_cndmask_b32_e64 v125, v219, v125, s[58:59]
	v_cmp_le_u32_e64 s[58:59], v245, v184
	v_add_u32_e32 v246, 0x73, v234
	v_cndmask_b32_e32 v120, v120, v0, vcc
	v_cmp_gt_u32_e32 vcc, v240, v233
	v_cndmask_b32_e64 v126, v219, v126, s[58:59]
	v_cmp_le_u32_e64 s[58:59], v246, v184
	s_or_b64 vcc, vcc, s[0:1]
	v_cndmask_b32_e32 v121, v121, v219, vcc
	v_cndmask_b32_e64 v127, v219, v127, s[58:59]
	v_cmp_gt_u32_e64 s[58:59], v234, v233
	v_cmp_gt_u32_e32 vcc, v241, v233
	s_or_b64 s[58:59], s[2:3], s[58:59]
	s_or_b64 vcc, vcc, s[52:53]
	v_cndmask_b32_e64 v168, v168, v0, s[58:59]
	v_cmp_ge_u32_e64 s[58:59], v234, v233
	v_cndmask_b32_e32 v122, v122, v219, vcc
	v_cmp_gt_u32_e32 vcc, v242, v233
	s_or_b64 s[58:59], s[2:3], s[58:59]
	s_or_b64 vcc, vcc, s[54:55]
	v_cndmask_b32_e64 v169, v169, v219, s[58:59]
	v_cmp_gt_u32_e64 s[58:59], v2, v233
	v_cndmask_b32_e32 v123, v123, v219, vcc
	v_cmp_gt_u32_e32 vcc, v243, v233
	s_or_b64 s[58:59], s[2:3], s[58:59]
	v_cndmask_b32_e64 v170, v170, v219, s[58:59]
	v_cndmask_b32_e32 v116, v116, v0, vcc
	v_cmp_le_u32_e32 vcc, v244, v233
	v_cmp_gt_u32_e64 s[58:59], v3, v233
	s_or_b64 s[58:59], s[2:3], s[58:59]
	v_cndmask_b32_e32 v117, v219, v117, vcc
	v_cmp_le_u32_e32 vcc, v245, v233
	v_cndmask_b32_e64 v171, v171, v219, s[58:59]
	s_movk_i32 s31, 0x207f
	v_cndmask_b32_e32 v118, v219, v118, vcc
	v_cmp_le_u32_e32 vcc, v246, v233
	s_mov_b32 s30, 0x800000
	s_mov_b32 s39, s74
	v_cndmask_b32_e32 v119, v219, v119, vcc
; DEV float shfl_xor_l(float v, int m, int lane) { return __int_as_float(__builtin_amdgcn_ds_bpermute((lane ^ m) << 2, __float_as_int(v))); }
; DEV float shfl_l(float v, int srclane) { return __int_as_float(__builtin_amdgcn_ds_bpermute(srclane << 2, __float_as_int(v))); }
; DEV float ex2(float x) { return __builtin_amdgcn_exp2f(x); }
; DEV void attn_item(const Params& p, int layer, int h, int qb, float lam, bf16_t* lds) {
;     ...
;     float al[2];
; #pragma unroll
;     for (int i = 0; i < 2; i++) {
;       float mx = -1e30f;
; #pragma unroll
;       for (int j = 0; j < 8; j++)
; #pragma unroll
;         for (int r = 0; r < 4; r++) mx = fmaxf(mx, s[i][j][r]);
;       mx = fmaxf(mx, shfl_xor_l(mx, 16, lane));
;       mx = fmaxf(mx, shfl_xor_l(mx, 32, lane));
;       const float mold = i == 0 ? mrun0 : mrun1;
;       const float mnew = (mx > mold + 8.f) ? mx : mold;
;       al[i] = ex2(mold - mnew);
;       float ps = 0.f;
; #pragma unroll
;       for (int j = 0; j < 8; j++)
; #pragma unroll
;         for (int r = 0; r < 4; r++) { const float pv = ex2(s[i][j][r] - mnew); s[i][j][r] = pv; ps += pv; }
;       if (i == 0) { mrun0 = mnew; lrun0 = lrun0 * al[0] + ps; } else { mrun1 = mnew; lrun1 = lrun1 * al[1] + ps; }
;     }
;     if (__builtin_amdgcn_ballot_w64(al[0] != 1.f || al[1] != 1.f) != 0ull) {
; #pragma unroll
;       for (int i = 0; i < 2; i++) {
;         float ao[4];
; #pragma unroll
;         for (int r = 0; r < 4; r++) ao[r] = shfl_l(al[i], lg * 4 + r);
; #pragma unroll
;         for (int je = 0; je < 8; je++)
; #pragma unroll
;           for (int r = 0; r < 4; r++) o[i][je][r] *= ao[r];
;       }
;     }
.LBB0_710:
	v_max3_f32 v0, v176, s68, v177
	v_max3_f32 v0, v0, v178, v179
	v_max3_f32 v2, v168, s68, v169
	v_max3_f32 v0, v0, v172, v173
	v_max3_f32 v2, v2, v170, v171
	v_max3_f32 v0, v0, v174, v175
	v_max3_f32 v2, v2, v164, v165
	v_max3_f32 v0, v0, v160, v161
	v_max3_f32 v2, v2, v166, v167
	v_max3_f32 v0, v0, v162, v163
	v_max3_f32 v2, v2, v152, v153
	v_max3_f32 v0, v0, v156, v157
	v_max3_f32 v2, v2, v154, v155
	v_max3_f32 v0, v0, v158, v159
	v_max3_f32 v2, v2, v148, v149
	v_max3_f32 v0, v0, v144, v145
	v_max3_f32 v2, v2, v150, v151
	v_max3_f32 v0, v0, v146, v147
	v_max3_f32 v2, v2, v136, v137
	v_max3_f32 v0, v0, v140, v141
	v_max3_f32 v2, v2, v138, v139
	v_max3_f32 v0, v0, v142, v143
	v_max3_f32 v2, v2, v132, v133
	v_max3_f32 v0, v0, v128, v129
	v_max3_f32 v2, v2, v134, v135
	v_max3_f32 v0, v0, v130, v131
	v_max3_f32 v2, v2, v120, v121
	v_max3_f32 v0, v0, v124, v125
	v_max3_f32 v2, v2, v122, v123
	v_max3_f32 v0, v0, v126, v127
	v_max3_f32 v2, v2, v116, v117
	v_max3_f32 v194, v2, v118, v119
	v_mov_b32_e32 v3, v0
	v_mov_b32_e32 v195, v0
	v_mov_b32_e32 v196, v194
	v_mov_b32_e32 v197, v194
	s_nop 1
	v_permlane16_swap_b32_e32 v3, v195
	v_permlane16_swap_b32_e32 v196, v197
	v_max_f32_e32 v0, v3, v195
	v_max_f32_e32 v194, v196, v197
	v_mov_b32_e32 v3, v0
	v_mov_b32_e32 v195, v0
	v_mov_b32_e32 v196, v194
	v_mov_b32_e32 v197, v194
	s_nop 1
	v_permlane32_swap_b32_e32 v3, v195
	v_permlane32_swap_b32_e32 v196, v197
	v_max_f32_e32 v0, v3, v195
	v_max_f32_e32 v196, v196, v197
	v_sub_f32_e32 v2, v192, v212
	v_sub_f32_e32 v3, v193, v206
	s_mov_b32 s0, 0x41000000
	v_pk_add_f32 v[194:195], v[2:3], s[0:1] op_sel_hi:[1,0]
	v_cmp_gt_f32_e32 vcc, v0, v195
	s_nop 1
	v_cndmask_b32_e32 v249, v3, v0, vcc
	v_cmp_gt_f32_e32 vcc, v196, v194
	s_nop 1
	v_cndmask_b32_e32 v248, v2, v196, vcc
	v_pk_add_f32 v[2:3], v[2:3], v[248:249] neg_lo:[0,1] neg_hi:[0,1]
	v_add_f32_e32 v193, v249, v206
	v_add_f32_e32 v192, v248, v212
	v_exp_f32_e32 v3, v3
	v_exp_f32_e32 v2, v2
	v_cmp_neq_f32_e32 vcc, 0, v249
	v_cmp_neq_f32_e64 s[0:1], 0, v248
	s_or_b64 vcc, s[0:1], vcc
	s_cbranch_vccz .Lattc_nofix
	v_sub_f32_e32 v176, v176, v249
	v_sub_f32_e32 v177, v177, v249
	v_sub_f32_e32 v178, v178, v249
	v_sub_f32_e32 v179, v179, v249
	v_sub_f32_e32 v168, v168, v248
	v_sub_f32_e32 v169, v169, v248
	v_sub_f32_e32 v170, v170, v248
	v_sub_f32_e32 v171, v171, v248
	v_sub_f32_e32 v172, v172, v249
	v_sub_f32_e32 v173, v173, v249
	v_sub_f32_e32 v174, v174, v249
	v_sub_f32_e32 v175, v175, v249
	v_sub_f32_e32 v164, v164, v248
	v_sub_f32_e32 v165, v165, v248
	v_sub_f32_e32 v166, v166, v248
	v_sub_f32_e32 v167, v167, v248
	v_sub_f32_e32 v160, v160, v249
	v_sub_f32_e32 v161, v161, v249
	v_sub_f32_e32 v162, v162, v249
	v_sub_f32_e32 v163, v163, v249
	v_sub_f32_e32 v152, v152, v248
	v_sub_f32_e32 v153, v153, v248
	v_sub_f32_e32 v154, v154, v248
	v_sub_f32_e32 v155, v155, v248
	v_sub_f32_e32 v156, v156, v249
	v_sub_f32_e32 v157, v157, v249
	v_sub_f32_e32 v158, v158, v249
	v_sub_f32_e32 v159, v159, v249
	v_sub_f32_e32 v148, v148, v248
	v_sub_f32_e32 v149, v149, v248
	v_sub_f32_e32 v150, v150, v248
	v_sub_f32_e32 v151, v151, v248
	v_sub_f32_e32 v144, v144, v249
	v_sub_f32_e32 v145, v145, v249
	v_sub_f32_e32 v146, v146, v249
	v_sub_f32_e32 v147, v147, v249
	v_sub_f32_e32 v136, v136, v248
	v_sub_f32_e32 v137, v137, v248
	v_sub_f32_e32 v138, v138, v248
	v_sub_f32_e32 v139, v139, v248
	v_sub_f32_e32 v140, v140, v249
	v_sub_f32_e32 v141, v141, v249
	v_sub_f32_e32 v142, v142, v249
	v_sub_f32_e32 v143, v143, v249
	v_sub_f32_e32 v132, v132, v248
	v_sub_f32_e32 v133, v133, v248
	v_sub_f32_e32 v134, v134, v248
	v_sub_f32_e32 v135, v135, v248
	v_sub_f32_e32 v128, v128, v249
	v_sub_f32_e32 v129, v129, v249
	v_sub_f32_e32 v130, v130, v249
	v_sub_f32_e32 v131, v131, v249
	v_sub_f32_e32 v120, v120, v248
	v_sub_f32_e32 v121, v121, v248
	v_sub_f32_e32 v122, v122, v248
	v_sub_f32_e32 v123, v123, v248
	v_sub_f32_e32 v124, v124, v249
	v_sub_f32_e32 v125, v125, v249
	v_sub_f32_e32 v126, v126, v249
	v_sub_f32_e32 v127, v127, v249
	v_sub_f32_e32 v116, v116, v248
	v_sub_f32_e32 v117, v117, v248
	v_sub_f32_e32 v118, v118, v248
	v_sub_f32_e32 v119, v119, v248
.Lattc_nofix:
	v_cmp_neq_f32_e32 vcc, 1.0, v3
	v_cmp_neq_f32_e64 s[0:1], 1.0, v2
	s_or_b64 vcc, s[0:1], vcc
	s_cbranch_vccz .LBB0_707
	ds_bpermute_b32 v194, v182, v3
	ds_bpermute_b32 v195, v227, v3
	ds_bpermute_b32 v196, v189, v3
	ds_bpermute_b32 v197, v187, v3
	s_waitcnt lgkmcnt(2)
	v_pk_mul_f32 v[100:101], v[100:101], v[194:195]
	v_pk_mul_f32 v[96:97], v[96:97], v[194:195]
	s_waitcnt lgkmcnt(0)
	v_pk_mul_f32 v[102:103], v[102:103], v[196:197]
	v_pk_mul_f32 v[98:99], v[98:99], v[196:197]
	v_pk_mul_f32 v[114:115], v[114:115], v[196:197]
	v_pk_mul_f32 v[112:113], v[112:113], v[194:195]
	v_pk_mul_f32 v[94:95], v[94:95], v[196:197]
	v_pk_mul_f32 v[92:93], v[92:93], v[194:195]
	v_pk_mul_f32 v[110:111], v[110:111], v[196:197]
	v_pk_mul_f32 v[108:109], v[108:109], v[194:195]
	v_pk_mul_f32 v[90:91], v[90:91], v[196:197]
	v_pk_mul_f32 v[88:89], v[88:89], v[194:195]
	v_pk_mul_f32 v[106:107], v[106:107], v[196:197]
	v_pk_mul_f32 v[104:105], v[104:105], v[194:195]
	v_pk_mul_f32 v[86:87], v[86:87], v[196:197]
	v_pk_mul_f32 v[84:85], v[84:85], v[194:195]
	ds_bpermute_b32 v194, v182, v2
	ds_bpermute_b32 v195, v227, v2
	ds_bpermute_b32 v196, v189, v2
	ds_bpermute_b32 v197, v187, v2
	s_waitcnt lgkmcnt(2)
	v_pk_mul_f32 v[80:81], v[80:81], v[194:195]
	v_pk_mul_f32 v[76:77], v[76:77], v[194:195]
	s_waitcnt lgkmcnt(0)
	v_pk_mul_f32 v[82:83], v[82:83], v[196:197]
	v_pk_mul_f32 v[78:79], v[78:79], v[196:197]
	v_pk_mul_f32 v[74:75], v[74:75], v[196:197]
	v_pk_mul_f32 v[72:73], v[72:73], v[194:195]
	v_pk_mul_f32 v[70:71], v[70:71], v[196:197]
	v_pk_mul_f32 v[68:69], v[68:69], v[194:195]
	v_pk_mul_f32 v[66:67], v[66:67], v[196:197]
	v_pk_mul_f32 v[64:65], v[64:65], v[194:195]
	v_pk_mul_f32 v[62:63], v[62:63], v[196:197]
	v_pk_mul_f32 v[60:61], v[60:61], v[194:195]
	v_pk_mul_f32 v[58:59], v[58:59], v[196:197]
	v_pk_mul_f32 v[56:57], v[56:57], v[194:195]
	v_pk_mul_f32 v[54:55], v[54:55], v[196:197]
	v_pk_mul_f32 v[52:53], v[52:53], v[194:195]
	s_branch .LBB0_707
